# attention step 3 reordered (PV before QK) so only reads of the not-yet-recycled LDS stage stay in flight across the tile barrier
# speedup vs baseline: 1.0002x; 1.0002x over previous
; #define KLOAD(kf_, base)                                                                       \
;   { _Pragma("unroll") for (int ks = 0; ks < NKS; ks++) kf_[ks] = *(const bf16x8*)((base) + kfo + ks * 32); }
; #define VLOAD(vf_, base)                                                                       \
;   { _Pragma("unroll") for (int q = 0; q < 4; q++) vf_[q] = *(const bf16x8*)((base) + vfo + (q >> 1) * 32 * VROW + (q & 1) * 32); }
; #define QKM(dst, kf_)                                                                          \
;   {                                                                                            \
;     _Pragma("unroll") for (int i = 0; i < 16; i++) dst[i] = 0.f;                               \
;     _Pragma("unroll") for (int ks = 0; ks < NKS; ks++) dst = MFMA(kf_[ks], qf[ks], dst);       \
;   }
; #define SB() __builtin_amdgcn_sched_barrier(0)
; template <int DK>
; DI void attn_core(const bf16x8 (&qf)[DK / 16], const short* Kg, const short* VTg, size_t ldvt, int ntiles, char* smem,
;                   f32x16 (&O)[2], float& lsum) {
;     ...
;   for (int t = 0; t < ntiles; t++) {
;     const int tn = t + 2 < ntiles ? t + 2 : ntiles - 1;
;     AGLOAD(tn);
;     const char* cur = smem + sc * ST;
;     const char* nxt = smem + sn * ST;
;     f32x16 Sn;
;     bf16x8 pa, pb, qa, qb;
;     bf16x8 kf[NKS], vf[4];
;     KLOAD(kf, cur + 32 * KROW);
;     SB();
;     SOFTMAX(Sc, pa, pb, l0);
;     SB();
;     QKM(Sn, kf);
;     SB();
;     KLOAD(kf, cur + 64 * KROW);
;     VLOAD(vf, cur);
;     SB();
;     SOFTMAX(Sn, qa, qb, l0);
;     SB();
;     QKM(Sc, kf);
;     PVM(vf, pa, pb);
;     SB();
;     KLOAD(kf, cur + 96 * KROW);
;     VLOAD(vf, cur + 64);
;     SB();
;     SOFTMAX(Sc, pa, pb, l0);
;     SB();
;     QKM(Sn, kf);
;     PVM(vf, qa, qb);
;     SB();
;     KLOAD(kf, nxt);
;     VLOAD(vf, cur + 128);
;     SB();
;     SOFTMAX(Sn, qa, qb, l0);
;     SB();
;     QKM(Sc, kf);
;     PVM(vf, pa, pb);
;     SB();
;     VLOAD(vf, cur + 192);
;     PVM(vf, qa, qb);
;     ASTORE(sw);
;     __syncthreads();
;     const int tmp = sc; sc = sn; sn = sw; sw = tmp;
;   }
.Lmla_prompt_loop:
	s_min_u32 s29, s21, 0x7d
	s_add_i32 s29, s29, 2
	s_mul_i32 s34, s29, 0x6000
	s_add_u32 s34, s8, s34
	s_addc_u32 s35, s9, 0
	s_lshl_b32 s30, s29, 8
	s_mul_i32 s29, s28, 0xac00
	v_add_u32_e32 v128, s29, v107
	v_add_u32_e32 v170, s29, v101
	s_mul_i32 s29, s22, 0xac00
	v_add_u32_e32 v109, s29, v107
	s_waitcnt lgkmcnt(6)
	v_mfma_f32_32x32x16_bf16 v[172:187], v[110:113], v[48:51], 0
	ds_read_b128 v[110:113], v128 offset:13312
	v_exp_f32_e32 v32, v32
	v_exp_f32_e32 v33, v33
	v_add_f32_e32 v108, v32, v108
	v_exp_f32_e32 v34, v34
	v_lshl_add_u64 v[188:189], v[92:93], 1, s[34:35]
	global_load_dwordx4 v[84:87], v[188:189], off
	s_waitcnt lgkmcnt(5)
	v_mfma_f32_32x32x16_bf16 v[172:187], v[114:117], v[52:55], v[172:187]
	ds_read_b128 v[114:117], v128 offset:13344
	v_add_f32_e32 v108, v33, v108
	v_cvt_pk_bf16_f32 v154, v32, v33
	v_exp_f32_e32 v35, v35
	v_add_f32_e32 v108, v34, v108
	v_lshl_add_u64 v[190:191], v[94:95], 1, s[34:35]
	global_load_dwordx4 v[72:75], v[190:191], off
	s_waitcnt lgkmcnt(5)
	v_mfma_f32_32x32x16_bf16 v[172:187], v[118:121], v[56:59], v[172:187]
	ds_read_b128 v[118:121], v128 offset:13376
	v_exp_f32_e32 v36, v36
	v_add_f32_e32 v108, v35, v108
	v_cvt_pk_bf16_f32 v155, v34, v35
	v_exp_f32_e32 v37, v37
	v_lshl_add_u64 v[192:193], v[96:97], 1, s[34:35]
	global_load_dwordx4 v[76:79], v[192:193], off
	s_waitcnt lgkmcnt(5)
	v_mfma_f32_32x32x16_bf16 v[172:187], v[122:125], v[60:63], v[172:187]
	ds_read_b128 v[122:125], v128 offset:13408
	v_add_f32_e32 v108, v36, v108
	v_exp_f32_e32 v38, v38
	v_add_f32_e32 v108, v37, v108
	v_cvt_pk_bf16_f32 v156, v36, v37
	v_lshl_add_u64 v[188:189], v[98:99], 0, s[30:31]
	global_load_dwordx4 v[80:83], v[188:189], off
	s_add_u32 s30, s30, s37
	s_waitcnt lgkmcnt(5)
	v_mfma_f32_32x32x16_bf16 v[172:187], v[130:133], v[64:67], v[172:187]
	ds_read_b128 v[130:133], v128 offset:13440
	v_exp_f32_e32 v39, v39
	v_add_f32_e32 v108, v38, v108
	v_exp_f32_e32 v40, v40
	v_add_f32_e32 v108, v39, v108
	v_lshl_add_u64 v[190:191], v[98:99], 0, s[30:31]
	global_load_dwordx4 v[88:91], v[190:191], off
	s_mul_i32 s29, s23, 0xac00
	s_waitcnt lgkmcnt(5)
	v_mfma_f32_32x32x16_bf16 v[172:187], v[134:137], v[68:71], v[172:187]
	ds_read_b128 v[134:137], v128 offset:13472
	v_cvt_pk_bf16_f32 v157, v38, v39
	v_exp_f32_e32 v41, v41
	v_add_f32_e32 v108, v40, v108
	v_exp_f32_e32 v42, v42
	s_waitcnt lgkmcnt(14)
	v_mfma_f32_32x32x16_bf16 v[0:15], v[138:141], v[162:165], v[0:15]
	ds_read_b128 v[138:141], v170 offset:26624
	v_add_f32_e32 v108, v41, v108
	v_cvt_pk_bf16_f32 v158, v40, v41
	v_exp_f32_e32 v43, v43
	v_add_f32_e32 v108, v42, v108
	s_waitcnt lgkmcnt(14)
	v_mfma_f32_32x32x16_bf16 v[16:31], v[146:149], v[162:165], v[16:31]
	ds_read_b128 v[146:149], v170 offset:35328
	v_exp_f32_e32 v44, v44
	v_add_f32_e32 v108, v43, v108
	v_cvt_pk_bf16_f32 v159, v42, v43
	v_exp_f32_e32 v45, v45
	s_waitcnt lgkmcnt(14)
	v_mfma_f32_32x32x16_bf16 v[0:15], v[142:145], v[166:169], v[0:15]
	ds_read_b128 v[142:145], v170 offset:26656
	v_add_f32_e32 v108, v44, v108
	v_exp_f32_e32 v46, v46
	v_add_f32_e32 v108, v45, v108
	v_cvt_pk_bf16_f32 v160, v44, v45
	s_waitcnt lgkmcnt(14)
	v_mfma_f32_32x32x16_bf16 v[16:31], v[150:153], v[166:169], v[16:31]
	ds_read_b128 v[150:153], v170 offset:35360
	v_exp_f32_e32 v47, v47
	v_add_f32_e32 v108, v46, v108
	v_add_f32_e32 v108, v47, v108
	v_cvt_pk_bf16_f32 v161, v46, v47
	s_waitcnt lgkmcnt(9)
	v_mfma_f32_32x32x16_bf16 v[32:47], v[110:113], v[48:51], 0
	ds_read_b128 v[110:113], v128 offset:19968
	v_exp_f32_e32 v172, v172
	v_exp_f32_e32 v173, v173
	v_add_f32_e32 v108, v172, v108
	v_exp_f32_e32 v174, v174
	s_waitcnt lgkmcnt(9)
	v_mfma_f32_32x32x16_bf16 v[32:47], v[114:117], v[52:55], v[32:47]
	ds_read_b128 v[114:117], v128 offset:20000
	v_add_f32_e32 v108, v173, v108
	v_cvt_pk_bf16_f32 v162, v172, v173
	v_exp_f32_e32 v175, v175
	v_add_f32_e32 v108, v174, v108
	s_waitcnt lgkmcnt(9)
	v_mfma_f32_32x32x16_bf16 v[32:47], v[118:121], v[56:59], v[32:47]
	ds_read_b128 v[118:121], v128 offset:20032
	v_exp_f32_e32 v176, v176
	v_add_f32_e32 v108, v175, v108
	v_cvt_pk_bf16_f32 v163, v174, v175
	v_exp_f32_e32 v177, v177
	s_waitcnt lgkmcnt(9)
	v_mfma_f32_32x32x16_bf16 v[32:47], v[122:125], v[60:63], v[32:47]
	ds_read_b128 v[122:125], v128 offset:20064
	v_add_f32_e32 v108, v176, v108
	v_exp_f32_e32 v178, v178
	v_add_f32_e32 v108, v177, v108
	v_cvt_pk_bf16_f32 v164, v176, v177
	s_waitcnt lgkmcnt(9)
	v_mfma_f32_32x32x16_bf16 v[32:47], v[130:133], v[64:67], v[32:47]
	ds_read_b128 v[130:133], v128 offset:20096
	v_exp_f32_e32 v179, v179
	v_add_f32_e32 v108, v178, v108
	v_exp_f32_e32 v180, v180
	v_add_f32_e32 v108, v179, v108
	s_waitcnt lgkmcnt(9)
	v_mfma_f32_32x32x16_bf16 v[32:47], v[134:137], v[68:71], v[32:47]
	ds_read_b128 v[134:137], v128 offset:20128
	v_cvt_pk_bf16_f32 v165, v178, v179
	v_exp_f32_e32 v181, v181
	v_add_f32_e32 v108, v180, v108
	v_exp_f32_e32 v182, v182
	s_waitcnt lgkmcnt(9)
	v_mfma_f32_32x32x16_bf16 v[0:15], v[138:141], v[154:157], v[0:15]
	ds_read_b128 v[138:141], v170 offset:26688
	v_add_f32_e32 v108, v181, v108
	v_cvt_pk_bf16_f32 v166, v180, v181
	v_exp_f32_e32 v183, v183
	v_add_f32_e32 v108, v182, v108
	s_waitcnt lgkmcnt(9)
	v_mfma_f32_32x32x16_bf16 v[16:31], v[146:149], v[154:157], v[16:31]
	ds_read_b128 v[146:149], v170 offset:35392
	v_exp_f32_e32 v184, v184
	v_add_f32_e32 v108, v183, v108
	v_cvt_pk_bf16_f32 v167, v182, v183
	v_exp_f32_e32 v185, v185
	s_waitcnt lgkmcnt(9)
	v_mfma_f32_32x32x16_bf16 v[0:15], v[142:145], v[158:161], v[0:15]
	ds_read_b128 v[142:145], v170 offset:26720
	v_add_f32_e32 v108, v184, v108
	v_exp_f32_e32 v186, v186
	v_add_f32_e32 v108, v185, v108
	v_cvt_pk_bf16_f32 v168, v184, v185
	s_waitcnt lgkmcnt(9)
; #define KLOAD(kf_, base)                                                                       \
;   { _Pragma("unroll") for (int ks = 0; ks < NKS; ks++) kf_[ks] = *(const bf16x8*)((base) + kfo + ks * 32); }
; #define VLOAD(vf_, base)                                                                       \
;   { _Pragma("unroll") for (int q = 0; q < 4; q++) vf_[q] = *(const bf16x8*)((base) + vfo + (q >> 1) * 32 * VROW + (q & 1) * 32); }
; #define QKM(dst, kf_)                                                                          \
;   {                                                                                            \
;     _Pragma("unroll") for (int i = 0; i < 16; i++) dst[i] = 0.f;                               \
;     _Pragma("unroll") for (int ks = 0; ks < NKS; ks++) dst = MFMA(kf_[ks], qf[ks], dst);       \
;   }
; #define SB() __builtin_amdgcn_sched_barrier(0)
; template <int DK>
; DI void attn_core(const bf16x8 (&qf)[DK / 16], const short* Kg, const short* VTg, size_t ldvt, int ntiles, char* smem,
;                   f32x16 (&O)[2], float& lsum) {
;     ...
;   for (int t = 0; t < ntiles; t++) {
;     const int tn = t + 2 < ntiles ? t + 2 : ntiles - 1;
;     AGLOAD(tn);
;     const char* cur = smem + sc * ST;
;     const char* nxt = smem + sn * ST;
;     f32x16 Sn;
;     bf16x8 pa, pb, qa, qb;
;     bf16x8 kf[NKS], vf[4];
;     KLOAD(kf, cur + 32 * KROW);
;     SB();
;     SOFTMAX(Sc, pa, pb, l0);
;     SB();
;     QKM(Sn, kf);
;     SB();
;     KLOAD(kf, cur + 64 * KROW);
;     VLOAD(vf, cur);
;     SB();
;     SOFTMAX(Sn, qa, qb, l0);
;     SB();
;     QKM(Sc, kf);
;     PVM(vf, pa, pb);
;     SB();
;     KLOAD(kf, cur + 96 * KROW);
;     VLOAD(vf, cur + 64);
;     SB();
;     SOFTMAX(Sc, pa, pb, l0);
;     SB();
;     QKM(Sn, kf);
;     PVM(vf, qa, qb);
;     SB();
;     KLOAD(kf, nxt);
;     VLOAD(vf, cur + 128);
;     SB();
;     SOFTMAX(Sn, qa, qb, l0);
;     SB();
;     QKM(Sc, kf);
;     PVM(vf, pa, pb);
;     SB();
;     VLOAD(vf, cur + 192);
;     PVM(vf, qa, qb);
;     ASTORE(sw);
;     __syncthreads();
;     const int tmp = sc; sc = sn; sn = sw; sw = tmp;
;   }
	v_mfma_f32_32x32x16_bf16 v[16:31], v[150:153], v[158:161], v[16:31]
	ds_read_b128 v[150:153], v170 offset:35424
	v_exp_f32_e32 v187, v187
	v_add_f32_e32 v108, v186, v108
	v_add_f32_e32 v108, v187, v108
	v_cvt_pk_bf16_f32 v169, v186, v187
	s_waitcnt lgkmcnt(9)
	v_mfma_f32_32x32x16_bf16 v[172:187], v[110:113], v[48:51], 0
	ds_read_b128 v[110:113], v109 offset:0
	v_exp_f32_e32 v32, v32
	v_exp_f32_e32 v33, v33
	v_add_f32_e32 v108, v32, v108
	v_exp_f32_e32 v34, v34
	s_waitcnt lgkmcnt(9)
	v_mfma_f32_32x32x16_bf16 v[172:187], v[114:117], v[52:55], v[172:187]
	ds_read_b128 v[114:117], v109 offset:32
	v_add_f32_e32 v108, v33, v108
	v_cvt_pk_bf16_f32 v154, v32, v33
	v_exp_f32_e32 v35, v35
	v_add_f32_e32 v108, v34, v108
	s_waitcnt lgkmcnt(9)
	v_mfma_f32_32x32x16_bf16 v[172:187], v[118:121], v[56:59], v[172:187]
	ds_read_b128 v[118:121], v109 offset:64
	v_exp_f32_e32 v36, v36
	v_add_f32_e32 v108, v35, v108
	v_cvt_pk_bf16_f32 v155, v34, v35
	v_exp_f32_e32 v37, v37
	s_waitcnt lgkmcnt(9)
	v_mfma_f32_32x32x16_bf16 v[172:187], v[122:125], v[60:63], v[172:187]
	ds_read_b128 v[122:125], v109 offset:96
	v_add_f32_e32 v108, v36, v108
	v_exp_f32_e32 v38, v38
	v_add_f32_e32 v108, v37, v108
	v_cvt_pk_bf16_f32 v156, v36, v37
	s_waitcnt lgkmcnt(9)
	v_mfma_f32_32x32x16_bf16 v[172:187], v[130:133], v[64:67], v[172:187]
	ds_read_b128 v[130:133], v109 offset:128
	v_exp_f32_e32 v39, v39
	v_add_f32_e32 v108, v38, v108
	v_exp_f32_e32 v40, v40
	v_add_f32_e32 v108, v39, v108
	s_waitcnt lgkmcnt(9)
	v_mfma_f32_32x32x16_bf16 v[172:187], v[134:137], v[68:71], v[172:187]
	ds_read_b128 v[134:137], v109 offset:160
	v_cvt_pk_bf16_f32 v157, v38, v39
	v_exp_f32_e32 v41, v41
	v_add_f32_e32 v108, v40, v108
	v_exp_f32_e32 v42, v42
	s_waitcnt lgkmcnt(9)
	v_mfma_f32_32x32x16_bf16 v[0:15], v[138:141], v[162:165], v[0:15]
	ds_read_b128 v[138:141], v170 offset:26752
	v_add_f32_e32 v108, v41, v108
	v_cvt_pk_bf16_f32 v158, v40, v41
	v_exp_f32_e32 v43, v43
	v_add_f32_e32 v108, v42, v108
	s_waitcnt lgkmcnt(9)
	v_mfma_f32_32x32x16_bf16 v[16:31], v[146:149], v[162:165], v[16:31]
	ds_read_b128 v[146:149], v170 offset:35456
	v_exp_f32_e32 v44, v44
	v_add_f32_e32 v108, v43, v108
	v_cvt_pk_bf16_f32 v159, v42, v43
	v_exp_f32_e32 v45, v45
	s_waitcnt lgkmcnt(9)
	v_mfma_f32_32x32x16_bf16 v[0:15], v[142:145], v[166:169], v[0:15]
	ds_read_b128 v[142:145], v170 offset:26784
	v_add_f32_e32 v108, v44, v108
	v_exp_f32_e32 v46, v46
	v_add_f32_e32 v108, v45, v108
	v_cvt_pk_bf16_f32 v160, v44, v45
	s_waitcnt lgkmcnt(9)
	v_mfma_f32_32x32x16_bf16 v[16:31], v[150:153], v[166:169], v[16:31]
	ds_read_b128 v[150:153], v170 offset:35488
	v_exp_f32_e32 v47, v47
	v_add_f32_e32 v108, v46, v108
	v_add_f32_e32 v108, v47, v108
	v_cvt_pk_bf16_f32 v161, v46, v47
	s_waitcnt lgkmcnt(3)
	v_mfma_f32_32x32x16_bf16 v[0:15], v[138:141], v[154:157], v[0:15]
	ds_read_b128 v[138:141], v170 offset:26816
	v_exp_f32_e32 v172, v172
	v_exp_f32_e32 v173, v173
	v_add_f32_e32 v108, v172, v108
	v_exp_f32_e32 v174, v174
	v_add_u32_e32 v188, s29, v104
	s_waitcnt vmcnt(4)
	ds_write_b128 v188, v[84:87]
	s_waitcnt lgkmcnt(4)
	v_mfma_f32_32x32x16_bf16 v[16:31], v[146:149], v[154:157], v[16:31]
	ds_read_b128 v[146:149], v170 offset:35520
	v_add_f32_e32 v108, v173, v108
	v_cvt_pk_bf16_f32 v162, v172, v173
	v_exp_f32_e32 v175, v175
	v_add_f32_e32 v108, v174, v108
	v_add_u32_e32 v189, s29, v105
	s_waitcnt vmcnt(3)
	ds_write_b128 v189, v[72:75]
	s_waitcnt lgkmcnt(5)
	v_mfma_f32_32x32x16_bf16 v[0:15], v[142:145], v[158:161], v[0:15]
	ds_read_b128 v[142:145], v170 offset:26848
	v_exp_f32_e32 v176, v176
	v_add_f32_e32 v108, v175, v108
	v_cvt_pk_bf16_f32 v163, v174, v175
	v_exp_f32_e32 v177, v177
	v_add_u32_e32 v190, s29, v106
	s_waitcnt vmcnt(2)
	ds_write_b128 v190, v[76:79]
	s_waitcnt lgkmcnt(6)
	v_mfma_f32_32x32x16_bf16 v[16:31], v[150:153], v[158:161], v[16:31]
	ds_read_b128 v[150:153], v170 offset:35552
	v_add_f32_e32 v108, v176, v108
	v_exp_f32_e32 v178, v178
	v_add_f32_e32 v108, v177, v108
	v_cvt_pk_bf16_f32 v164, v176, v177
	v_add_u32_e32 v191, s29, v100
	s_waitcnt vmcnt(1)
	ds_write_b128 v191, v[80:83] offset:26624
	s_waitcnt lgkmcnt(14)
	v_mfma_f32_32x32x16_bf16 v[32:47], v[110:113], v[48:51], 0
	ds_read_b128 v[110:113], v109 offset:6656
	v_exp_f32_e32 v179, v179
	v_add_f32_e32 v108, v178, v108
	v_exp_f32_e32 v180, v180
	v_add_f32_e32 v108, v179, v108
	s_waitcnt vmcnt(0)
	ds_write_b128 v191, v[88:91] offset:35328
	s_waitcnt lgkmcnt(14)
	v_mfma_f32_32x32x16_bf16 v[32:47], v[114:117], v[52:55], v[32:47]
	ds_read_b128 v[114:117], v109 offset:6688
	v_cvt_pk_bf16_f32 v165, v178, v179
	v_exp_f32_e32 v181, v181
	v_add_f32_e32 v108, v180, v108
	v_exp_f32_e32 v182, v182
	s_waitcnt lgkmcnt(14)
	v_mfma_f32_32x32x16_bf16 v[32:47], v[118:121], v[56:59], v[32:47]
	ds_read_b128 v[118:121], v109 offset:6720
	v_add_f32_e32 v108, v181, v108
	v_cvt_pk_bf16_f32 v166, v180, v181
	v_exp_f32_e32 v183, v183
	v_add_f32_e32 v108, v182, v108
	s_waitcnt lgkmcnt(14)
	v_mfma_f32_32x32x16_bf16 v[32:47], v[122:125], v[60:63], v[32:47]
	ds_read_b128 v[122:125], v109 offset:6752
	v_exp_f32_e32 v184, v184
	v_add_f32_e32 v108, v183, v108
	v_cvt_pk_bf16_f32 v167, v182, v183
	v_exp_f32_e32 v185, v185
	s_waitcnt lgkmcnt(14)
	v_mfma_f32_32x32x16_bf16 v[32:47], v[130:133], v[64:67], v[32:47]
	ds_read_b128 v[130:133], v109 offset:6784
	v_add_f32_e32 v108, v184, v108
	v_exp_f32_e32 v186, v186
	v_add_f32_e32 v108, v185, v108
	v_cvt_pk_bf16_f32 v168, v184, v185
	s_waitcnt lgkmcnt(14)
	v_mfma_f32_32x32x16_bf16 v[32:47], v[134:137], v[68:71], v[32:47]
	ds_read_b128 v[134:137], v109 offset:6816
	v_exp_f32_e32 v187, v187
	v_add_f32_e32 v108, v186, v108
	v_add_f32_e32 v108, v187, v108
	v_cvt_pk_bf16_f32 v169, v186, v187
	s_add_i32 s21, s21, 1
	s_mov_b32 s30, s28
	s_mov_b32 s28, s22
	s_mov_b32 s22, s23
	s_mov_b32 s23, s30
	s_cmpk_lg_i32 s21, 0x80
	s_waitcnt lgkmcnt(5)
	s_barrier
; DI int my_tid() { int t = threadIdx.x; asm volatile("" : "+v"(t)); return t; }
; DI float bf_lo(unsigned u) { return __uint_as_float(u << 16); }
; DI float bf_hi(unsigned u) { return __uint_as_float(u & 0xffff0000u); }
; template <int DK>
; DI void attn_core(const bf16x8 (&qf)[DK / 16], const short* Kg, const short* VTg, size_t ldvt, int ntiles, char* smem,
;                   f32x16 (&O)[2], float& lsum) {
;     ...
;   lsum = l0;
;     ...
; }
; DI void attn_store(const f32x16 (&O)[2], float lsum, int tok, int col0, const short* gate, short* o, char* smem) {
;   const int tid = my_tid(), lane = tid & 63, w = tid >> 6, r = lane & 31, h = lane >> 5;
;   float l = lsum + __shfl_xor(lsum, 32);
;   float inv = __builtin_amdgcn_rcpf(l);
;   float* pw = (float*)(smem + w * (32 * 68 * 4));
;   const int tokw = tok - r;
;   const int ch = lane & 7;
;   u32x4 gpre[4];
; #pragma unroll
;   for (int j = 0; j < 4; j++) gpre[j] = *(const u32x4*)(gate + (size_t)(tokw + j * 8 + (lane >> 3)) * 1024 + col0 + ch * 8);
; #pragma unroll
;   for (int dt = 0; dt < 2; dt++)
; #pragma unroll
;     for (int q = 0; q < 4; q++) {
;       f32x4 t = {O[dt][q * 4 + 0] * inv, O[dt][q * 4 + 1] * inv, O[dt][q * 4 + 2] * inv, O[dt][q * 4 + 3] * inv};
;       *(f32x4*)(pw + r * 68 + dt * 32 + 8 * q + 4 * h) = t;
;     }
;   asm volatile("s_waitcnt lgkmcnt(0)" ::: "memory");
; #pragma unroll
;   for (int j = 0; j < 4; j++) {
;     const int row = j * 8 + (lane >> 3);
;     const size_t g = (size_t)(tokw + row) * 1024 + col0 + ch * 8;
;     const u32x4 gv = gpre[j];
;     const f32x4 a = *(const f32x4*)(pw + row * 68 + ch * 8), c = *(const f32x4*)(pw + row * 68 + ch * 8 + 4);
;     u32x4 ov;
;     ov[0] = pack_bf16(a[0] * bf_lo(gv[0]), a[1] * bf_hi(gv[0]));
;     ov[1] = pack_bf16(a[2] * bf_lo(gv[1]), a[3] * bf_hi(gv[1]));
;     ov[2] = pack_bf16(c[0] * bf_lo(gv[2]), c[1] * bf_hi(gv[2]));
;     ov[3] = pack_bf16(c[2] * bf_lo(gv[3]), c[3] * bf_hi(gv[3]));
;     __builtin_nontemporal_store(ov, (u32x4*)(o + g));
;   }
;   __syncthreads();
; }
; DI void run_phase(PRef p, int ph, char* smem, int noatom) {
;     ...
;         for (int li = l; li < 96; li += nl) {
;           const int u = xj + 8 * (li >> 5);
;           mla_item(p, j, 0, u >> 1, (u & 1) * 32 + (li & 31), smem);
;         }
	s_cbranch_scc1 .Lmla_prompt_loop
	s_waitcnt lgkmcnt(0)
	s_barrier
	v_mfma_f32_32x32x16_bf16 v[0:15], v[138:141], v[162:165], v[0:15]
	v_mfma_f32_32x32x16_bf16 v[16:31], v[146:149], v[162:165], v[16:31]
	v_mfma_f32_32x32x16_bf16 v[0:15], v[142:145], v[166:169], v[0:15]
	v_mfma_f32_32x32x16_bf16 v[16:31], v[150:153], v[166:169], v[16:31]
	s_nop 10
	ds_bpermute_b32 v33, v103, v108
	s_lshl_b32 s8, s16, 6
	v_mov_b32_e32 v57, v196
	s_ashr_i32 s9, s8, 31
	v_lshrrev_b32_e32 v32, 6, v57
	v_and_b32_e32 v58, 31, v57
	s_waitcnt lgkmcnt(0)
	v_add_f32_e32 v56, v108, v33
	v_mul_lo_u32 v59, v32, s38
	v_sub_u32_e32 v32, v102, v58
	v_bfe_u32 v60, v57, 3, 3
	s_lshl_b64 s[8:9], s[8:9], 1
	v_lshlrev_b32_e32 v33, 3, v57
	v_add_u32_e32 v32, v60, v32
	s_add_u32 s22, s14, s8
	v_and_b32_e32 v61, 56, v33
	s_addc_u32 s23, s15, s9
	v_lshlrev_b32_e32 v128, 1, v61
	v_ashrrev_i32_e32 v33, 31, v32
	v_lshl_add_u64 v[34:35], s[22:23], 0, v[128:129]
	v_lshlrev_b64 v[54:55], 11, v[32:33]
	v_lshl_add_u64 v[36:37], v[34:35], 0, v[54:55]
	global_load_dwordx4 v[44:47], v[36:37], off
	v_add_u32_e32 v36, 8, v32
	v_ashrrev_i32_e32 v37, 31, v36
	v_lshlrev_b64 v[52:53], 11, v[36:37]
	v_lshl_add_u64 v[36:37], v[34:35], 0, v[52:53]
	global_load_dwordx4 v[40:43], v[36:37], off
	v_add_u32_e32 v36, 16, v32
	v_ashrrev_i32_e32 v37, 31, v36
	v_lshlrev_b64 v[50:51], 11, v[36:37]
	v_lshl_add_u64 v[36:37], v[34:35], 0, v[50:51]
	global_load_dwordx4 v[36:39], v[36:37], off
	v_add_u32_e32 v32, 24, v32
	v_ashrrev_i32_e32 v33, 31, v32
	v_lshlrev_b64 v[48:49], 11, v[32:33]
	v_lshl_add_u64 v[32:33], v[34:35], 0, v[48:49]
	global_load_dwordx4 v[32:35], v[32:33], off
	v_rcp_f32_e32 v56, v56
	v_lshrrev_b32_e32 v57, 1, v57
	v_mul_u32_u24_e32 v58, 0x110, v58
	v_and_b32_e32 v57, 16, v57
	v_add3_u32 v57, v59, v58, v57
	v_pk_mul_f32 v[0:1], v[0:1], v[56:57] op_sel_hi:[1,0]
	v_pk_mul_f32 v[2:3], v[2:3], v[56:57] op_sel_hi:[1,0]
	ds_write_b128 v57, v[0:3]
	v_pk_mul_f32 v[0:1], v[4:5], v[56:57] op_sel_hi:[1,0]
	v_pk_mul_f32 v[2:3], v[6:7], v[56:57] op_sel_hi:[1,0]
	ds_write_b128 v57, v[0:3] offset:32
	v_pk_mul_f32 v[0:1], v[8:9], v[56:57] op_sel_hi:[1,0]
	v_pk_mul_f32 v[2:3], v[10:11], v[56:57] op_sel_hi:[1,0]
	ds_write_b128 v57, v[0:3] offset:64
	v_pk_mul_f32 v[0:1], v[12:13], v[56:57] op_sel_hi:[1,0]
	v_pk_mul_f32 v[2:3], v[14:15], v[56:57] op_sel_hi:[1,0]
	ds_write_b128 v57, v[0:3] offset:96
	v_pk_mul_f32 v[0:1], v[16:17], v[56:57] op_sel_hi:[1,0]
	v_pk_mul_f32 v[2:3], v[18:19], v[56:57] op_sel_hi:[1,0]
	ds_write_b128 v57, v[0:3] offset:128
	v_pk_mul_f32 v[0:1], v[20:21], v[56:57] op_sel_hi:[1,0]
	v_pk_mul_f32 v[2:3], v[22:23], v[56:57] op_sel_hi:[1,0]
	ds_write_b128 v57, v[0:3] offset:160
	v_pk_mul_f32 v[0:1], v[24:25], v[56:57] op_sel_hi:[1,0]
	v_pk_mul_f32 v[2:3], v[26:27], v[56:57] op_sel_hi:[1,0]
	ds_write_b128 v57, v[0:3] offset:192
	v_pk_mul_f32 v[0:1], v[28:29], v[56:57] op_sel_hi:[1,0]
	v_pk_mul_f32 v[2:3], v[30:31], v[56:57] op_sel_hi:[1,0]
	ds_write_b128 v57, v[0:3] offset:224
	v_lshl_or_b32 v2, v61, 2, v59
	s_movk_i32 s36, 0x110
	s_waitcnt lgkmcnt(0)
	v_mad_u32_u24 v12, v60, s36, v2
	ds_read_b128 v[2:5], v12
	ds_read_b128 v[6:9], v12 offset:16
	s_add_u32 s8, s18, s8
	s_addc_u32 s9, s19, s9
	v_lshl_add_u64 v[0:1], s[8:9], 0, v[128:129]
	v_readlane_b32 s8, v226, 12
	s_add_i32 s20, s20, s8
	s_cmpk_gt_i32 s20, 0x5f
	s_waitcnt vmcnt(3)
	v_lshlrev_b32_e32 v10, 16, v44
	v_and_b32_e32 v11, 0xffff0000, v44
	s_waitcnt lgkmcnt(1)
	v_pk_mul_f32 v[2:3], v[2:3], v[10:11]
	v_lshlrev_b32_e32 v10, 16, v45
	v_and_b32_e32 v11, 0xffff0000, v45
	v_pk_mul_f32 v[4:5], v[4:5], v[10:11]
	v_cvt_pk_bf16_f32 v2, v2, v3
	v_cvt_pk_bf16_f32 v3, v4, v5
	v_lshlrev_b32_e32 v4, 16, v46
	v_and_b32_e32 v5, 0xffff0000, v46
	s_waitcnt lgkmcnt(0)
	v_pk_mul_f32 v[4:5], v[6:7], v[4:5]
	v_lshlrev_b32_e32 v6, 16, v47
	v_and_b32_e32 v7, 0xffff0000, v47
	v_pk_mul_f32 v[6:7], v[8:9], v[6:7]
	v_cvt_pk_bf16_f32 v4, v4, v5
	v_cvt_pk_bf16_f32 v5, v6, v7
	v_lshl_add_u64 v[6:7], v[0:1], 0, v[54:55]
	global_store_dwordx4 v[6:7], v[2:5], off nt
	ds_read_b128 v[2:5], v12 offset:2176
	ds_read_b128 v[6:9], v12 offset:2192
	s_waitcnt vmcnt(3)
	v_lshlrev_b32_e32 v10, 16, v40
	v_and_b32_e32 v11, 0xffff0000, v40
	s_waitcnt lgkmcnt(1)
	v_pk_mul_f32 v[2:3], v[2:3], v[10:11]
	v_lshlrev_b32_e32 v10, 16, v41
	v_and_b32_e32 v11, 0xffff0000, v41
	v_pk_mul_f32 v[4:5], v[4:5], v[10:11]
	v_cvt_pk_bf16_f32 v2, v2, v3
	v_cvt_pk_bf16_f32 v3, v4, v5
	v_lshlrev_b32_e32 v4, 16, v42
	v_and_b32_e32 v5, 0xffff0000, v42
	s_waitcnt lgkmcnt(0)
	v_pk_mul_f32 v[4:5], v[6:7], v[4:5]
	v_lshlrev_b32_e32 v6, 16, v43
	v_and_b32_e32 v7, 0xffff0000, v43
	v_pk_mul_f32 v[6:7], v[8:9], v[6:7]
	v_cvt_pk_bf16_f32 v4, v4, v5
	v_cvt_pk_bf16_f32 v5, v6, v7
	v_lshl_add_u64 v[6:7], v[0:1], 0, v[52:53]
	global_store_dwordx4 v[6:7], v[2:5], off nt
	ds_read_b128 v[2:5], v12 offset:4352
	ds_read_b128 v[6:9], v12 offset:4368
	s_waitcnt vmcnt(3)
	v_lshlrev_b32_e32 v10, 16, v36
	v_and_b32_e32 v11, 0xffff0000, v36
	s_waitcnt lgkmcnt(1)
	v_pk_mul_f32 v[2:3], v[2:3], v[10:11]
	v_lshlrev_b32_e32 v10, 16, v37
	v_and_b32_e32 v11, 0xffff0000, v37
	v_pk_mul_f32 v[4:5], v[4:5], v[10:11]
	v_cvt_pk_bf16_f32 v2, v2, v3
	v_cvt_pk_bf16_f32 v3, v4, v5
	v_lshlrev_b32_e32 v4, 16, v38
	v_and_b32_e32 v5, 0xffff0000, v38
	s_waitcnt lgkmcnt(0)
	v_pk_mul_f32 v[4:5], v[6:7], v[4:5]
	v_lshlrev_b32_e32 v6, 16, v39
	v_and_b32_e32 v7, 0xffff0000, v39
	v_pk_mul_f32 v[6:7], v[8:9], v[6:7]
	v_cvt_pk_bf16_f32 v4, v4, v5
	v_cvt_pk_bf16_f32 v5, v6, v7
	v_lshl_add_u64 v[6:7], v[0:1], 0, v[50:51]
	global_store_dwordx4 v[6:7], v[2:5], off nt
	ds_read_b128 v[2:5], v12 offset:6528
	ds_read_b128 v[6:9], v12 offset:6544
	s_waitcnt vmcnt(3)
	v_lshlrev_b32_e32 v10, 16, v32
	v_and_b32_e32 v11, 0xffff0000, v32
	v_lshl_add_u64 v[0:1], v[0:1], 0, v[48:49]
	s_waitcnt lgkmcnt(1)
	v_pk_mul_f32 v[2:3], v[2:3], v[10:11]
	v_lshlrev_b32_e32 v10, 16, v33
	v_and_b32_e32 v11, 0xffff0000, v33
	v_pk_mul_f32 v[4:5], v[4:5], v[10:11]
	v_cvt_pk_bf16_f32 v2, v2, v3
	v_cvt_pk_bf16_f32 v3, v4, v5
	v_lshlrev_b32_e32 v4, 16, v34
	v_and_b32_e32 v5, 0xffff0000, v34
	s_waitcnt lgkmcnt(0)
	v_pk_mul_f32 v[4:5], v[6:7], v[4:5]
	v_lshlrev_b32_e32 v6, 16, v35
	v_and_b32_e32 v7, 0xffff0000, v35
	v_pk_mul_f32 v[6:7], v[8:9], v[6:7]
	v_cvt_pk_bf16_f32 v4, v4, v5
	v_cvt_pk_bf16_f32 v5, v6, v7
	global_store_dwordx4 v[0:1], v[2:5], off nt
	s_barrier
	s_cbranch_scc0 .LBB0_165

; #define KLOAD(kf_, base)                                                                       \
;   { _Pragma("unroll") for (int ks = 0; ks < NKS; ks++) kf_[ks] = *(const bf16x8*)((base) + kfo + ks * 32); }
; #define VLOAD(vf_, base)                                                                       \
;   { _Pragma("unroll") for (int q = 0; q < 4; q++) vf_[q] = *(const bf16x8*)((base) + vfo + (q >> 1) * 32 * VROW + (q & 1) * 32); }
; #define QKM(dst, kf_)                                                                          \
;   {                                                                                            \
;     _Pragma("unroll") for (int i = 0; i < 16; i++) dst[i] = 0.f;                               \
;     _Pragma("unroll") for (int ks = 0; ks < NKS; ks++) dst = MFMA(kf_[ks], qf[ks], dst);       \
;   }
; #define SB() __builtin_amdgcn_sched_barrier(0)
; template <int DK>
; DI void attn_core(const bf16x8 (&qf)[DK / 16], const short* Kg, const short* VTg, size_t ldvt, int ntiles, char* smem,
;                   f32x16 (&O)[2], float& lsum) {
;     ...
;   for (int t = 0; t < ntiles; t++) {
;     const int tn = t + 2 < ntiles ? t + 2 : ntiles - 1;
;     AGLOAD(tn);
;     const char* cur = smem + sc * ST;
;     const char* nxt = smem + sn * ST;
;     f32x16 Sn;
;     bf16x8 pa, pb, qa, qb;
;     bf16x8 kf[NKS], vf[4];
;     KLOAD(kf, cur + 32 * KROW);
;     SB();
;     SOFTMAX(Sc, pa, pb, l0);
;     SB();
;     QKM(Sn, kf);
;     SB();
;     KLOAD(kf, cur + 64 * KROW);
;     VLOAD(vf, cur);
;     SB();
;     SOFTMAX(Sn, qa, qb, l0);
;     SB();
;     QKM(Sc, kf);
;     PVM(vf, pa, pb);
;     SB();
;     KLOAD(kf, cur + 96 * KROW);
;     VLOAD(vf, cur + 64);
;     SB();
;     SOFTMAX(Sc, pa, pb, l0);
;     SB();
;     QKM(Sn, kf);
;     PVM(vf, qa, qb);
;     SB();
;     KLOAD(kf, nxt);
;     VLOAD(vf, cur + 128);
;     SB();
;     SOFTMAX(Sn, qa, qb, l0);
;     SB();
;     QKM(Sc, kf);
;     PVM(vf, pa, pb);
;     SB();
;     VLOAD(vf, cur + 192);
;     PVM(vf, qa, qb);
;     ASTORE(sw);
;     __syncthreads();
;     const int tmp = sc; sc = sn; sn = sw; sw = tmp;
;   }
.Lmla_sample_loop:
	s_add_i32 s35, s23, 2
	s_min_u32 s35, s35, s14
	s_mul_i32 s36, s35, 0x6000
	s_mul_hi_u32 s37, s35, 0x6000
	s_add_u32 s36, s8, s36
	s_addc_u32 s37, s9, s37
	s_lshl_b32 s30, s35, 8
	s_mul_i32 s35, s15, 0xac00
	v_add_u32_e32 v128, s35, v107
	v_add_u32_e32 v170, s35, v101
	s_mul_i32 s35, s34, 0xac00
	v_add_u32_e32 v109, s35, v107
	s_waitcnt lgkmcnt(6)
	v_mfma_f32_32x32x16_bf16 v[172:187], v[110:113], v[48:51], 0
	ds_read_b128 v[110:113], v128 offset:13312
	v_exp_f32_e32 v32, v32
	v_exp_f32_e32 v33, v33
	v_add_f32_e32 v108, v32, v108
	v_exp_f32_e32 v34, v34
	v_lshl_add_u64 v[188:189], v[92:93], 1, s[36:37]
	global_load_dwordx4 v[84:87], v[188:189], off
	s_waitcnt lgkmcnt(5)
	v_mfma_f32_32x32x16_bf16 v[172:187], v[114:117], v[52:55], v[172:187]
	ds_read_b128 v[114:117], v128 offset:13344
	v_add_f32_e32 v108, v33, v108
	v_cvt_pk_bf16_f32 v154, v32, v33
	v_exp_f32_e32 v35, v35
	v_add_f32_e32 v108, v34, v108
	v_lshl_add_u64 v[190:191], v[94:95], 1, s[36:37]
	global_load_dwordx4 v[72:75], v[190:191], off
	s_waitcnt lgkmcnt(5)
	v_mfma_f32_32x32x16_bf16 v[172:187], v[118:121], v[56:59], v[172:187]
	ds_read_b128 v[118:121], v128 offset:13376
	v_exp_f32_e32 v36, v36
	v_add_f32_e32 v108, v35, v108
	v_cvt_pk_bf16_f32 v155, v34, v35
	v_exp_f32_e32 v37, v37
	v_lshl_add_u64 v[192:193], v[96:97], 1, s[36:37]
	global_load_dwordx4 v[76:79], v[192:193], off
	s_waitcnt lgkmcnt(5)
	v_mfma_f32_32x32x16_bf16 v[172:187], v[122:125], v[60:63], v[172:187]
	ds_read_b128 v[122:125], v128 offset:13408
	v_add_f32_e32 v108, v36, v108
	v_exp_f32_e32 v38, v38
	v_add_f32_e32 v108, v37, v108
	v_cvt_pk_bf16_f32 v156, v36, v37
	v_lshl_add_u64 v[188:189], v[98:99], 0, s[30:31]
	global_load_dwordx4 v[80:83], v[188:189], off
	s_add_u32 s30, s30, s39
	s_waitcnt lgkmcnt(5)
	v_mfma_f32_32x32x16_bf16 v[172:187], v[130:133], v[64:67], v[172:187]
	ds_read_b128 v[130:133], v128 offset:13440
	v_exp_f32_e32 v39, v39
	v_add_f32_e32 v108, v38, v108
	v_exp_f32_e32 v40, v40
	v_add_f32_e32 v108, v39, v108
	v_lshl_add_u64 v[190:191], v[98:99], 0, s[30:31]
	global_load_dwordx4 v[88:91], v[190:191], off
	s_mul_i32 s35, s28, 0xac00
	s_waitcnt lgkmcnt(5)
	v_mfma_f32_32x32x16_bf16 v[172:187], v[134:137], v[68:71], v[172:187]
	ds_read_b128 v[134:137], v128 offset:13472
	v_cvt_pk_bf16_f32 v157, v38, v39
	v_exp_f32_e32 v41, v41
	v_add_f32_e32 v108, v40, v108
	v_exp_f32_e32 v42, v42
	s_waitcnt lgkmcnt(14)
	v_mfma_f32_32x32x16_bf16 v[0:15], v[138:141], v[162:165], v[0:15]
	ds_read_b128 v[138:141], v170 offset:26624
	v_add_f32_e32 v108, v41, v108
	v_cvt_pk_bf16_f32 v158, v40, v41
	v_exp_f32_e32 v43, v43
	v_add_f32_e32 v108, v42, v108
	s_waitcnt lgkmcnt(14)
	v_mfma_f32_32x32x16_bf16 v[16:31], v[146:149], v[162:165], v[16:31]
	ds_read_b128 v[146:149], v170 offset:35328
	v_exp_f32_e32 v44, v44
	v_add_f32_e32 v108, v43, v108
	v_cvt_pk_bf16_f32 v159, v42, v43
	v_exp_f32_e32 v45, v45
	s_waitcnt lgkmcnt(14)
	v_mfma_f32_32x32x16_bf16 v[0:15], v[142:145], v[166:169], v[0:15]
	ds_read_b128 v[142:145], v170 offset:26656
	v_add_f32_e32 v108, v44, v108
	v_exp_f32_e32 v46, v46
	v_add_f32_e32 v108, v45, v108
	v_cvt_pk_bf16_f32 v160, v44, v45
	s_waitcnt lgkmcnt(14)
	v_mfma_f32_32x32x16_bf16 v[16:31], v[150:153], v[166:169], v[16:31]
	ds_read_b128 v[150:153], v170 offset:35360
	v_exp_f32_e32 v47, v47
	v_add_f32_e32 v108, v46, v108
	v_add_f32_e32 v108, v47, v108
	v_cvt_pk_bf16_f32 v161, v46, v47
	s_waitcnt lgkmcnt(9)
	v_mfma_f32_32x32x16_bf16 v[32:47], v[110:113], v[48:51], 0
	ds_read_b128 v[110:113], v128 offset:19968
	v_exp_f32_e32 v172, v172
	v_exp_f32_e32 v173, v173
	v_add_f32_e32 v108, v172, v108
	v_exp_f32_e32 v174, v174
	s_waitcnt lgkmcnt(9)
	v_mfma_f32_32x32x16_bf16 v[32:47], v[114:117], v[52:55], v[32:47]
	ds_read_b128 v[114:117], v128 offset:20000
	v_add_f32_e32 v108, v173, v108
	v_cvt_pk_bf16_f32 v162, v172, v173
	v_exp_f32_e32 v175, v175
	v_add_f32_e32 v108, v174, v108
	s_waitcnt lgkmcnt(9)
	v_mfma_f32_32x32x16_bf16 v[32:47], v[118:121], v[56:59], v[32:47]
	ds_read_b128 v[118:121], v128 offset:20032
	v_exp_f32_e32 v176, v176
	v_add_f32_e32 v108, v175, v108
	v_cvt_pk_bf16_f32 v163, v174, v175
	v_exp_f32_e32 v177, v177
	s_waitcnt lgkmcnt(9)
	v_mfma_f32_32x32x16_bf16 v[32:47], v[122:125], v[60:63], v[32:47]
	ds_read_b128 v[122:125], v128 offset:20064
	v_add_f32_e32 v108, v176, v108
	v_exp_f32_e32 v178, v178
	v_add_f32_e32 v108, v177, v108
	v_cvt_pk_bf16_f32 v164, v176, v177
	s_waitcnt lgkmcnt(9)
	v_mfma_f32_32x32x16_bf16 v[32:47], v[130:133], v[64:67], v[32:47]
	ds_read_b128 v[130:133], v128 offset:20096
	v_exp_f32_e32 v179, v179
	v_add_f32_e32 v108, v178, v108
	v_exp_f32_e32 v180, v180
	v_add_f32_e32 v108, v179, v108
	s_waitcnt lgkmcnt(9)
	v_mfma_f32_32x32x16_bf16 v[32:47], v[134:137], v[68:71], v[32:47]
	ds_read_b128 v[134:137], v128 offset:20128
	v_cvt_pk_bf16_f32 v165, v178, v179
	v_exp_f32_e32 v181, v181
	v_add_f32_e32 v108, v180, v108
	v_exp_f32_e32 v182, v182
	s_waitcnt lgkmcnt(9)
	v_mfma_f32_32x32x16_bf16 v[0:15], v[138:141], v[154:157], v[0:15]
	ds_read_b128 v[138:141], v170 offset:26688
	v_add_f32_e32 v108, v181, v108
	v_cvt_pk_bf16_f32 v166, v180, v181
	v_exp_f32_e32 v183, v183
	v_add_f32_e32 v108, v182, v108
	s_waitcnt lgkmcnt(9)
	v_mfma_f32_32x32x16_bf16 v[16:31], v[146:149], v[154:157], v[16:31]
	ds_read_b128 v[146:149], v170 offset:35392
	v_exp_f32_e32 v184, v184
	v_add_f32_e32 v108, v183, v108
	v_cvt_pk_bf16_f32 v167, v182, v183
	v_exp_f32_e32 v185, v185
	s_waitcnt lgkmcnt(9)
	v_mfma_f32_32x32x16_bf16 v[0:15], v[142:145], v[158:161], v[0:15]
	ds_read_b128 v[142:145], v170 offset:26720
	v_add_f32_e32 v108, v184, v108
	v_exp_f32_e32 v186, v186
	v_add_f32_e32 v108, v185, v108
	v_cvt_pk_bf16_f32 v168, v184, v185
	s_waitcnt lgkmcnt(9)
; #define KLOAD(kf_, base)                                                                       \
;   { _Pragma("unroll") for (int ks = 0; ks < NKS; ks++) kf_[ks] = *(const bf16x8*)((base) + kfo + ks * 32); }
; #define VLOAD(vf_, base)                                                                       \
;   { _Pragma("unroll") for (int q = 0; q < 4; q++) vf_[q] = *(const bf16x8*)((base) + vfo + (q >> 1) * 32 * VROW + (q & 1) * 32); }
; #define QKM(dst, kf_)                                                                          \
;   {                                                                                            \
;     _Pragma("unroll") for (int i = 0; i < 16; i++) dst[i] = 0.f;                               \
;     _Pragma("unroll") for (int ks = 0; ks < NKS; ks++) dst = MFMA(kf_[ks], qf[ks], dst);       \
;   }
; #define SB() __builtin_amdgcn_sched_barrier(0)
; template <int DK>
; DI void attn_core(const bf16x8 (&qf)[DK / 16], const short* Kg, const short* VTg, size_t ldvt, int ntiles, char* smem,
;                   f32x16 (&O)[2], float& lsum) {
;     ...
;     SOFTMAX(Sc, pa, pb, l0);
;     SB();
;     QKM(Sn, kf);
;     PVM(vf, qa, qb);
;     SB();
;     KLOAD(kf, nxt);
;     VLOAD(vf, cur + 128);
;     SB();
;     SOFTMAX(Sn, qa, qb, l0);
;     SB();
;     QKM(Sc, kf);
;     PVM(vf, pa, pb);
;     SB();
;     VLOAD(vf, cur + 192);
;     PVM(vf, qa, qb);
;     ASTORE(sw);
;     __syncthreads();
;     const int tmp = sc; sc = sn; sn = sw; sw = tmp;
	v_mfma_f32_32x32x16_bf16 v[16:31], v[150:153], v[158:161], v[16:31]
	ds_read_b128 v[150:153], v170 offset:35424
	v_exp_f32_e32 v187, v187
	v_add_f32_e32 v108, v186, v108
	v_add_f32_e32 v108, v187, v108
	v_cvt_pk_bf16_f32 v169, v186, v187
	s_waitcnt lgkmcnt(9)
	v_mfma_f32_32x32x16_bf16 v[172:187], v[110:113], v[48:51], 0
	ds_read_b128 v[110:113], v109 offset:0
	v_exp_f32_e32 v32, v32
	v_exp_f32_e32 v33, v33
	v_add_f32_e32 v108, v32, v108
	v_exp_f32_e32 v34, v34
	s_waitcnt lgkmcnt(9)
	v_mfma_f32_32x32x16_bf16 v[172:187], v[114:117], v[52:55], v[172:187]
	ds_read_b128 v[114:117], v109 offset:32
	v_add_f32_e32 v108, v33, v108
	v_cvt_pk_bf16_f32 v154, v32, v33
	v_exp_f32_e32 v35, v35
	v_add_f32_e32 v108, v34, v108
	s_waitcnt lgkmcnt(9)
	v_mfma_f32_32x32x16_bf16 v[172:187], v[118:121], v[56:59], v[172:187]
	ds_read_b128 v[118:121], v109 offset:64
	v_exp_f32_e32 v36, v36
	v_add_f32_e32 v108, v35, v108
	v_cvt_pk_bf16_f32 v155, v34, v35
	v_exp_f32_e32 v37, v37
	s_waitcnt lgkmcnt(9)
	v_mfma_f32_32x32x16_bf16 v[172:187], v[122:125], v[60:63], v[172:187]
	ds_read_b128 v[122:125], v109 offset:96
	v_add_f32_e32 v108, v36, v108
	v_exp_f32_e32 v38, v38
	v_add_f32_e32 v108, v37, v108
	v_cvt_pk_bf16_f32 v156, v36, v37
	s_waitcnt lgkmcnt(9)
	v_mfma_f32_32x32x16_bf16 v[172:187], v[130:133], v[64:67], v[172:187]
	ds_read_b128 v[130:133], v109 offset:128
	v_exp_f32_e32 v39, v39
	v_add_f32_e32 v108, v38, v108
	v_exp_f32_e32 v40, v40
	v_add_f32_e32 v108, v39, v108
	s_waitcnt lgkmcnt(9)
	v_mfma_f32_32x32x16_bf16 v[172:187], v[134:137], v[68:71], v[172:187]
	ds_read_b128 v[134:137], v109 offset:160
	v_cvt_pk_bf16_f32 v157, v38, v39
	v_exp_f32_e32 v41, v41
	v_add_f32_e32 v108, v40, v108
	v_exp_f32_e32 v42, v42
	s_waitcnt lgkmcnt(9)
	v_mfma_f32_32x32x16_bf16 v[0:15], v[138:141], v[162:165], v[0:15]
	ds_read_b128 v[138:141], v170 offset:26752
	v_add_f32_e32 v108, v41, v108
	v_cvt_pk_bf16_f32 v158, v40, v41
	v_exp_f32_e32 v43, v43
	v_add_f32_e32 v108, v42, v108
	s_waitcnt lgkmcnt(9)
	v_mfma_f32_32x32x16_bf16 v[16:31], v[146:149], v[162:165], v[16:31]
	ds_read_b128 v[146:149], v170 offset:35456
	v_exp_f32_e32 v44, v44
	v_add_f32_e32 v108, v43, v108
	v_cvt_pk_bf16_f32 v159, v42, v43
	v_exp_f32_e32 v45, v45
	s_waitcnt lgkmcnt(9)
	v_mfma_f32_32x32x16_bf16 v[0:15], v[142:145], v[166:169], v[0:15]
	ds_read_b128 v[142:145], v170 offset:26784
	v_add_f32_e32 v108, v44, v108
	v_exp_f32_e32 v46, v46
	v_add_f32_e32 v108, v45, v108
	v_cvt_pk_bf16_f32 v160, v44, v45
	s_waitcnt lgkmcnt(9)
	v_mfma_f32_32x32x16_bf16 v[16:31], v[150:153], v[166:169], v[16:31]
	ds_read_b128 v[150:153], v170 offset:35488
	v_exp_f32_e32 v47, v47
	v_add_f32_e32 v108, v46, v108
	v_add_f32_e32 v108, v47, v108
	v_cvt_pk_bf16_f32 v161, v46, v47
	s_waitcnt lgkmcnt(3)
	v_mfma_f32_32x32x16_bf16 v[0:15], v[138:141], v[154:157], v[0:15]
	ds_read_b128 v[138:141], v170 offset:26816
	v_exp_f32_e32 v172, v172
	v_exp_f32_e32 v173, v173
	v_add_f32_e32 v108, v172, v108
	v_exp_f32_e32 v174, v174
	v_add_u32_e32 v188, s35, v104
	s_waitcnt vmcnt(4)
	ds_write_b128 v188, v[84:87]
	s_waitcnt lgkmcnt(4)
	v_mfma_f32_32x32x16_bf16 v[16:31], v[146:149], v[154:157], v[16:31]
	ds_read_b128 v[146:149], v170 offset:35520
	v_add_f32_e32 v108, v173, v108
	v_cvt_pk_bf16_f32 v162, v172, v173
	v_exp_f32_e32 v175, v175
	v_add_f32_e32 v108, v174, v108
	v_add_u32_e32 v189, s35, v105
	s_waitcnt vmcnt(3)
	ds_write_b128 v189, v[72:75]
	s_waitcnt lgkmcnt(5)
	v_mfma_f32_32x32x16_bf16 v[0:15], v[142:145], v[158:161], v[0:15]
	ds_read_b128 v[142:145], v170 offset:26848
	v_exp_f32_e32 v176, v176
	v_add_f32_e32 v108, v175, v108
	v_cvt_pk_bf16_f32 v163, v174, v175
	v_exp_f32_e32 v177, v177
	v_add_u32_e32 v190, s35, v106
	s_waitcnt vmcnt(2)
	ds_write_b128 v190, v[76:79]
	s_waitcnt lgkmcnt(6)
	v_mfma_f32_32x32x16_bf16 v[16:31], v[150:153], v[158:161], v[16:31]
	ds_read_b128 v[150:153], v170 offset:35552
	v_add_f32_e32 v108, v176, v108
	v_exp_f32_e32 v178, v178
	v_add_f32_e32 v108, v177, v108
	v_cvt_pk_bf16_f32 v164, v176, v177
	v_add_u32_e32 v191, s35, v100
	s_waitcnt vmcnt(1)
	ds_write_b128 v191, v[80:83] offset:26624
	s_waitcnt lgkmcnt(14)
	v_mfma_f32_32x32x16_bf16 v[32:47], v[110:113], v[48:51], 0
	ds_read_b128 v[110:113], v109 offset:6656
	v_exp_f32_e32 v179, v179
	v_add_f32_e32 v108, v178, v108
	v_exp_f32_e32 v180, v180
	v_add_f32_e32 v108, v179, v108
	s_waitcnt vmcnt(0)
	ds_write_b128 v191, v[88:91] offset:35328
	s_waitcnt lgkmcnt(14)
	v_mfma_f32_32x32x16_bf16 v[32:47], v[114:117], v[52:55], v[32:47]
	ds_read_b128 v[114:117], v109 offset:6688
	v_cvt_pk_bf16_f32 v165, v178, v179
	v_exp_f32_e32 v181, v181
	v_add_f32_e32 v108, v180, v108
	v_exp_f32_e32 v182, v182
	s_waitcnt lgkmcnt(14)
	v_mfma_f32_32x32x16_bf16 v[32:47], v[118:121], v[56:59], v[32:47]
	ds_read_b128 v[118:121], v109 offset:6720
	v_add_f32_e32 v108, v181, v108
	v_cvt_pk_bf16_f32 v166, v180, v181
	v_exp_f32_e32 v183, v183
	v_add_f32_e32 v108, v182, v108
	s_waitcnt lgkmcnt(14)
	v_mfma_f32_32x32x16_bf16 v[32:47], v[122:125], v[60:63], v[32:47]
	ds_read_b128 v[122:125], v109 offset:6752
	v_exp_f32_e32 v184, v184
	v_add_f32_e32 v108, v183, v108
	v_cvt_pk_bf16_f32 v167, v182, v183
	v_exp_f32_e32 v185, v185
	s_waitcnt lgkmcnt(14)
	v_mfma_f32_32x32x16_bf16 v[32:47], v[130:133], v[64:67], v[32:47]
	ds_read_b128 v[130:133], v109 offset:6784
	v_add_f32_e32 v108, v184, v108
	v_exp_f32_e32 v186, v186
	v_add_f32_e32 v108, v185, v108
	v_cvt_pk_bf16_f32 v168, v184, v185
	s_waitcnt lgkmcnt(14)
	v_mfma_f32_32x32x16_bf16 v[32:47], v[134:137], v[68:71], v[32:47]
	ds_read_b128 v[134:137], v109 offset:6816
	v_exp_f32_e32 v187, v187
	v_add_f32_e32 v108, v186, v108
	v_add_f32_e32 v108, v187, v108
	v_cvt_pk_bf16_f32 v169, v186, v187
	s_add_i32 s23, s23, 1
	s_mov_b32 s30, s15
	s_mov_b32 s15, s34
	s_mov_b32 s34, s28
	s_mov_b32 s28, s30
	s_cmp_lg_u32 s29, s23
	s_waitcnt lgkmcnt(5)
	s_barrier
; DI int my_tid() { int t = threadIdx.x; asm volatile("" : "+v"(t)); return t; }
; DI float bf_lo(unsigned u) { return __uint_as_float(u << 16); }
; DI float bf_hi(unsigned u) { return __uint_as_float(u & 0xffff0000u); }
; DI void attn_store(const f32x16 (&O)[2], float lsum, int tok, int col0, const short* gate, short* o, char* smem) {
;   const int tid = my_tid(), lane = tid & 63, w = tid >> 6, r = lane & 31, h = lane >> 5;
;   float l = lsum + __shfl_xor(lsum, 32);
;   float inv = __builtin_amdgcn_rcpf(l);
;   float* pw = (float*)(smem + w * (32 * 68 * 4));
;   const int tokw = tok - r;
;   const int ch = lane & 7;
;   u32x4 gpre[4];
; #pragma unroll
;   for (int j = 0; j < 4; j++) gpre[j] = *(const u32x4*)(gate + (size_t)(tokw + j * 8 + (lane >> 3)) * 1024 + col0 + ch * 8);
; #pragma unroll
;   for (int dt = 0; dt < 2; dt++)
; #pragma unroll
;     for (int q = 0; q < 4; q++) {
;       f32x4 t = {O[dt][q * 4 + 0] * inv, O[dt][q * 4 + 1] * inv, O[dt][q * 4 + 2] * inv, O[dt][q * 4 + 3] * inv};
;       *(f32x4*)(pw + r * 68 + dt * 32 + 8 * q + 4 * h) = t;
;     }
;   asm volatile("s_waitcnt lgkmcnt(0)" ::: "memory");
; #pragma unroll
;   for (int j = 0; j < 4; j++) {
;     const int row = j * 8 + (lane >> 3);
;     const size_t g = (size_t)(tokw + row) * 1024 + col0 + ch * 8;
;     const u32x4 gv = gpre[j];
;     const f32x4 a = *(const f32x4*)(pw + row * 68 + ch * 8), c = *(const f32x4*)(pw + row * 68 + ch * 8 + 4);
;     u32x4 ov;
;     ov[0] = pack_bf16(a[0] * bf_lo(gv[0]), a[1] * bf_hi(gv[0]));
;     ov[1] = pack_bf16(a[2] * bf_lo(gv[1]), a[3] * bf_hi(gv[1]));
;     ov[2] = pack_bf16(c[0] * bf_lo(gv[2]), c[1] * bf_hi(gv[2]));
;     ov[3] = pack_bf16(c[2] * bf_lo(gv[3]), c[3] * bf_hi(gv[3]));
;     __builtin_nontemporal_store(ov, (u32x4*)(o + g));
;   }
;   __syncthreads();
	s_cbranch_scc1 .Lmla_sample_loop
	s_waitcnt lgkmcnt(0)
	s_barrier
	v_mfma_f32_32x32x16_bf16 v[0:15], v[138:141], v[162:165], v[0:15]
	v_mfma_f32_32x32x16_bf16 v[16:31], v[146:149], v[162:165], v[16:31]
	v_mfma_f32_32x32x16_bf16 v[0:15], v[142:145], v[166:169], v[0:15]
	v_mfma_f32_32x32x16_bf16 v[16:31], v[150:153], v[166:169], v[16:31]
	s_nop 10
	ds_bpermute_b32 v33, v103, v108
	s_lshl_b32 s8, s16, 6
	v_mov_b32_e32 v57, v196
	s_ashr_i32 s9, s8, 31
	v_lshrrev_b32_e32 v32, 6, v57
	v_and_b32_e32 v58, 31, v57
	s_waitcnt lgkmcnt(0)
	v_add_f32_e32 v56, v108, v33
	v_mul_lo_u32 v59, v32, s38
	v_sub_u32_e32 v32, v102, v58
	v_bfe_u32 v60, v57, 3, 3
	s_lshl_b64 s[8:9], s[8:9], 1
	v_lshlrev_b32_e32 v33, 3, v57
	v_add_u32_e32 v32, v60, v32
	s_add_u32 s14, s18, s8
	v_and_b32_e32 v61, 56, v33
	s_addc_u32 s15, s19, s9
	v_lshlrev_b32_e32 v128, 1, v61
	v_ashrrev_i32_e32 v33, 31, v32
	v_lshl_add_u64 v[34:35], s[14:15], 0, v[128:129]
	v_lshlrev_b64 v[54:55], 11, v[32:33]
	v_lshl_add_u64 v[36:37], v[34:35], 0, v[54:55]
	global_load_dwordx4 v[44:47], v[36:37], off
	v_add_u32_e32 v36, 8, v32
	v_ashrrev_i32_e32 v37, 31, v36
	v_lshlrev_b64 v[52:53], 11, v[36:37]
	v_lshl_add_u64 v[36:37], v[34:35], 0, v[52:53]
	global_load_dwordx4 v[40:43], v[36:37], off
	v_add_u32_e32 v36, 16, v32
	v_ashrrev_i32_e32 v37, 31, v36
	v_lshlrev_b64 v[50:51], 11, v[36:37]
	v_lshl_add_u64 v[36:37], v[34:35], 0, v[50:51]
	global_load_dwordx4 v[36:39], v[36:37], off
	v_add_u32_e32 v32, 24, v32
	v_ashrrev_i32_e32 v33, 31, v32
	v_lshlrev_b64 v[48:49], 11, v[32:33]
	v_lshl_add_u64 v[32:33], v[34:35], 0, v[48:49]
	global_load_dwordx4 v[32:35], v[32:33], off
	v_rcp_f32_e32 v56, v56
	v_lshrrev_b32_e32 v57, 1, v57
	v_mul_u32_u24_e32 v58, 0x110, v58
	v_and_b32_e32 v57, 16, v57
	v_add3_u32 v57, v59, v58, v57
	v_pk_mul_f32 v[0:1], v[0:1], v[56:57] op_sel_hi:[1,0]
	v_pk_mul_f32 v[2:3], v[2:3], v[56:57] op_sel_hi:[1,0]
	ds_write_b128 v57, v[0:3]
	v_pk_mul_f32 v[0:1], v[4:5], v[56:57] op_sel_hi:[1,0]
	v_pk_mul_f32 v[2:3], v[6:7], v[56:57] op_sel_hi:[1,0]
	ds_write_b128 v57, v[0:3] offset:32
	v_pk_mul_f32 v[0:1], v[8:9], v[56:57] op_sel_hi:[1,0]
	v_pk_mul_f32 v[2:3], v[10:11], v[56:57] op_sel_hi:[1,0]
	ds_write_b128 v57, v[0:3] offset:64
	v_pk_mul_f32 v[0:1], v[12:13], v[56:57] op_sel_hi:[1,0]
	v_pk_mul_f32 v[2:3], v[14:15], v[56:57] op_sel_hi:[1,0]
	ds_write_b128 v57, v[0:3] offset:96
	v_pk_mul_f32 v[0:1], v[16:17], v[56:57] op_sel_hi:[1,0]
	v_pk_mul_f32 v[2:3], v[18:19], v[56:57] op_sel_hi:[1,0]
	ds_write_b128 v57, v[0:3] offset:128
	v_pk_mul_f32 v[0:1], v[20:21], v[56:57] op_sel_hi:[1,0]
	v_pk_mul_f32 v[2:3], v[22:23], v[56:57] op_sel_hi:[1,0]
	ds_write_b128 v57, v[0:3] offset:160
	v_pk_mul_f32 v[0:1], v[24:25], v[56:57] op_sel_hi:[1,0]
	v_pk_mul_f32 v[2:3], v[26:27], v[56:57] op_sel_hi:[1,0]
	ds_write_b128 v57, v[0:3] offset:192
	v_pk_mul_f32 v[0:1], v[28:29], v[56:57] op_sel_hi:[1,0]
	v_pk_mul_f32 v[2:3], v[30:31], v[56:57] op_sel_hi:[1,0]
	ds_write_b128 v57, v[0:3] offset:224
	v_lshl_or_b32 v2, v61, 2, v59
	s_movk_i32 s36, 0x110
	s_waitcnt lgkmcnt(0)
	v_mad_u32_u24 v12, v60, s36, v2
	ds_read_b128 v[2:5], v12
	ds_read_b128 v[6:9], v12 offset:16
	s_add_u32 s8, s20, s8
	s_addc_u32 s9, s21, s9
	v_lshl_add_u64 v[0:1], s[8:9], 0, v[128:129]
	v_readlane_b32 s8, v226, 12
	s_add_i32 s22, s22, s8
	s_cmpk_gt_i32 s22, 0x17f
	s_waitcnt vmcnt(3)
	v_lshlrev_b32_e32 v10, 16, v44
	v_and_b32_e32 v11, 0xffff0000, v44
	s_waitcnt lgkmcnt(1)
	v_pk_mul_f32 v[2:3], v[2:3], v[10:11]
	v_lshlrev_b32_e32 v10, 16, v45
	v_and_b32_e32 v11, 0xffff0000, v45
	v_pk_mul_f32 v[4:5], v[4:5], v[10:11]
	v_cvt_pk_bf16_f32 v2, v2, v3
	v_cvt_pk_bf16_f32 v3, v4, v5
	v_lshlrev_b32_e32 v4, 16, v46
	v_and_b32_e32 v5, 0xffff0000, v46
	s_waitcnt lgkmcnt(0)
	v_pk_mul_f32 v[4:5], v[6:7], v[4:5]
	v_lshlrev_b32_e32 v6, 16, v47
	v_and_b32_e32 v7, 0xffff0000, v47
	v_pk_mul_f32 v[6:7], v[8:9], v[6:7]
	v_cvt_pk_bf16_f32 v4, v4, v5
	v_cvt_pk_bf16_f32 v5, v6, v7
	v_lshl_add_u64 v[6:7], v[0:1], 0, v[54:55]
	global_store_dwordx4 v[6:7], v[2:5], off nt
	ds_read_b128 v[2:5], v12 offset:2176
	ds_read_b128 v[6:9], v12 offset:2192
	s_waitcnt vmcnt(3)
	v_lshlrev_b32_e32 v10, 16, v40
	v_and_b32_e32 v11, 0xffff0000, v40
	s_waitcnt lgkmcnt(1)
	v_pk_mul_f32 v[2:3], v[2:3], v[10:11]
	v_lshlrev_b32_e32 v10, 16, v41
	v_and_b32_e32 v11, 0xffff0000, v41
	v_pk_mul_f32 v[4:5], v[4:5], v[10:11]
	v_cvt_pk_bf16_f32 v2, v2, v3
	v_cvt_pk_bf16_f32 v3, v4, v5
	v_lshlrev_b32_e32 v4, 16, v42
	v_and_b32_e32 v5, 0xffff0000, v42
	s_waitcnt lgkmcnt(0)
	v_pk_mul_f32 v[4:5], v[6:7], v[4:5]
	v_lshlrev_b32_e32 v6, 16, v43
	v_and_b32_e32 v7, 0xffff0000, v43
	v_pk_mul_f32 v[6:7], v[8:9], v[6:7]
	v_cvt_pk_bf16_f32 v4, v4, v5
	v_cvt_pk_bf16_f32 v5, v6, v7
	v_lshl_add_u64 v[6:7], v[0:1], 0, v[52:53]
	global_store_dwordx4 v[6:7], v[2:5], off nt
	ds_read_b128 v[2:5], v12 offset:4352
	ds_read_b128 v[6:9], v12 offset:4368
	s_waitcnt vmcnt(3)
	v_lshlrev_b32_e32 v10, 16, v36
	v_and_b32_e32 v11, 0xffff0000, v36
	s_waitcnt lgkmcnt(1)
	v_pk_mul_f32 v[2:3], v[2:3], v[10:11]
	v_lshlrev_b32_e32 v10, 16, v37
	v_and_b32_e32 v11, 0xffff0000, v37
	v_pk_mul_f32 v[4:5], v[4:5], v[10:11]
	v_cvt_pk_bf16_f32 v2, v2, v3
	v_cvt_pk_bf16_f32 v3, v4, v5
	v_lshlrev_b32_e32 v4, 16, v38
	v_and_b32_e32 v5, 0xffff0000, v38
	s_waitcnt lgkmcnt(0)
	v_pk_mul_f32 v[4:5], v[6:7], v[4:5]
	v_lshlrev_b32_e32 v6, 16, v39
	v_and_b32_e32 v7, 0xffff0000, v39
	v_pk_mul_f32 v[6:7], v[8:9], v[6:7]
	v_cvt_pk_bf16_f32 v4, v4, v5
	v_cvt_pk_bf16_f32 v5, v6, v7
	v_lshl_add_u64 v[6:7], v[0:1], 0, v[50:51]
	global_store_dwordx4 v[6:7], v[2:5], off nt
	ds_read_b128 v[2:5], v12 offset:6528
	ds_read_b128 v[6:9], v12 offset:6544
	s_waitcnt vmcnt(3)
	v_lshlrev_b32_e32 v10, 16, v32
	v_and_b32_e32 v11, 0xffff0000, v32
	v_lshl_add_u64 v[0:1], v[0:1], 0, v[48:49]
	s_waitcnt lgkmcnt(1)
	v_pk_mul_f32 v[2:3], v[2:3], v[10:11]
	v_lshlrev_b32_e32 v10, 16, v33
	v_and_b32_e32 v11, 0xffff0000, v33
	v_pk_mul_f32 v[4:5], v[4:5], v[10:11]
	v_cvt_pk_bf16_f32 v2, v2, v3
	v_cvt_pk_bf16_f32 v3, v4, v5
	v_lshlrev_b32_e32 v4, 16, v34
	v_and_b32_e32 v5, 0xffff0000, v34
	s_waitcnt lgkmcnt(0)
	v_pk_mul_f32 v[4:5], v[6:7], v[4:5]
	v_lshlrev_b32_e32 v6, 16, v35
	v_and_b32_e32 v7, 0xffff0000, v35
	v_pk_mul_f32 v[6:7], v[8:9], v[6:7]
	v_cvt_pk_bf16_f32 v4, v4, v5
	v_cvt_pk_bf16_f32 v5, v6, v7
	global_store_dwordx4 v[0:1], v[2:5], off nt
	s_barrier
	s_cbranch_scc0 .LBB0_170
